# stack i + one static s_setprio 1 for waves 4-7 before the two attention main loops (reset at the queue loop head)
# speedup vs baseline: 1.0036x; 1.0021x over previous
; __device__ __forceinline__ void mixer_queue_phase(const Params& p, int l, char* lds) {
;     ...
;     for (;;) {
;         if (threadIdx.x == 0) *slot = (int)atomicAdd(ctr, 1u);
;         __syncthreads();
;         const int item = *slot;
;         __syncthreads();
;         if (item >= total) break;
.LBB0_3391:
	s_setprio 0
	s_and_saveexec_b64 s[0:1], s[72:73]
	s_cbranch_execz .LBB0_3395
	s_mov_b64 s[38:39], exec
	v_mbcnt_lo_u32_b32 v0, s38, 0
	v_mbcnt_hi_u32_b32 v0, s39, v0
	v_cmp_eq_u32_e32 vcc, 0, v0
	s_and_saveexec_b64 s[2:3], vcc
	s_cbranch_execz .LBB0_3394
	s_bcnt1_i32_b64 s6, s[38:39]
	v_mov_b32_e32 v1, s6
	global_atomic_add v1, v179, v1, s[62:63] offset:64 sc0

; #define LAS __attribute__((address_space(3)))
; __device__ __forceinline__ int otid() { int t = threadIdx.x; asm volatile("" : "+v"(t)); return t; }
; __device__ __forceinline__ int v_rd_base(int lane) { return ((lane & 3) << 3) | (((lane >> 2) & 3) << 6) | (((lane >> 4) & 1) << 5) | (((lane >> 5) & 1) << 8); }
; template <int LDQ, int LDK, int LDV> ...
;     ...
;     const int tid = otid(), wid = __builtin_amdgcn_readfirstlane(tid >> 6), lane = tid & 63, r32 = lane & 31, hi = lane >> 5;
;     char* V_lds = lds; char* K_lds = lds + 3 * SHM_V;
;     LAS unsigned char* ldsl = (LAS unsigned char*)(uintptr_t)lds;
;     float* wsl = (float*)(lds + 3 * SHM_V + 3 * SHM_K) + wid * 64; float* li_l = wsl; float* al_l = wsl + 32;
;     float m_reg = -1e30f, l_reg = 0; f32x16 o[4] = {}; bf16x8 qr[ND0];
;     const bf16_t* Qw = Qb + (size_t)(wid * 32 + r32) * LDQ + hi * 8;
; #pragma unroll
;     for (int d0 = 0; d0 < ND0; ++d0) qr[d0] = *reinterpret_cast<const bf16x8*>(Qw + d0 * 16);
;     int voff[2], koff[KCH];
; #pragma unroll
;     for (int i = 0; i < 2; ++i) { const int L = (tid + 512 * i) * 16, sub = L >> 9, within = L & 511; const int kk = (sub >> 2) * 8 + (within >> 6), c = (sub & 3) * 32 + ((within & 63) >> 1);
;         const int k = (kk & ~0xC) | ((kk & 4) << 1) | ((kk & 8) >> 1); voff[i] = k * LDV + c; }
; #pragma unroll
;     for (int i = 0; i < KCH; ++i) { const int L = (tid + 512 * i) * 16, row = L / (DQK * 2), cb = (L % (DQK * 2)) ^ ((row & 7) << 4), col = cb >> 1; koff[i] = row * LDK + col; }
;     const int vb0 = (int)(uintptr_t)V_lds + v_rd_base(lane);
;     ...
;     f32x16 pA0, pA1, pB0, pB1; float mnA, mnB, alA, alB; bf16x8 pa0, pa1, pa2, pa3; const int NT = seq / 64;
;     STAGE(0, 0); STAGE(1, 64); asm volatile("s_waitcnt vmcnt(0)" ::: "memory"); __syncthreads();
.LBB0_3442:
	s_or_b64 exec, exec, s[38:39]
	s_and_saveexec_b64 s[6:7], s[0:1]
	s_xor_b64 s[0:1], exec, s[6:7]
	v_lshl_add_u32 v132, v2, 8, v224
	s_or_saveexec_b64 s[0:1], s[0:1]
	v_mov_b32_e32 v133, 0
	v_mov_b32_e32 v160, 4
	v_mov_b32_e32 v161, 0
	s_xor_b64 exec, exec, s[0:1]
	v_lshlrev_b32_e32 v4, 8, v4
	v_lshl_or_b32 v132, v3, 11, v4
	v_mov_b32_e32 v161, 0x800
	v_mov_b32_e32 v160, 36
	s_or_b64 exec, exec, s[0:1]
	v_cndmask_b32_e32 v2, v2, v3, vcc
	v_lshrrev_b32_e32 v3, 2, v154
	v_lshl_or_b32 v2, v2, 1, v3
	s_movk_i32 s0, 0x900
	v_mov_b32_e32 v8, v176
	v_mul_lo_u32 v162, v2, s0
	s_movk_i32 s7, 0x70
	v_readfirstlane_b32 s0, v8
	s_ashr_i32 s6, s0, 6
	s_and_b32 s0, s0, 0x3fffffc0
	s_lshl_b32 s0, s0, 2
	v_and_b32_e32 v155, 31, v8
	s_add_i32 s1, s0, 0
	s_lshl_b32 s0, s6, 5
	v_or_b32_e32 v2, s0, v155
	v_ashrrev_i32_e32 v3, 31, v2
	v_bfe_u32 v156, v8, 5, 1
	v_lshlrev_b64 v[2:3], 8, v[2:3]
	v_lshl_add_u64 v[0:1], v[0:1], 0, v[2:3]
	v_lshlrev_b32_e32 v178, 4, v156
	v_lshl_add_u64 v[0:1], v[0:1], 0, v[178:179]
	global_load_dwordx4 v[124:127], v[0:1], off
	global_load_dwordx4 v[120:123], v[0:1], off offset:32
	global_load_dwordx4 v[116:119], v[0:1], off offset:64
	global_load_dwordx4 v[112:115], v[0:1], off offset:96
	global_load_dwordx4 v[108:111], v[0:1], off offset:128
	global_load_dwordx4 v[104:107], v[0:1], off offset:160
	global_load_dwordx4 v[100:103], v[0:1], off offset:192
	global_load_dwordx4 v[96:99], v[0:1], off offset:224
	v_and_b32_e32 v1, 0x60, v8
	v_lshlrev_b32_e32 v2, 3, v8
	v_bfe_u32 v0, v8, 2, 2
	v_and_or_b32 v1, v2, 24, v1
	v_lshrrev_b32_e32 v2, 1, v8
	v_and_or_b32 v0, v2, 8, v0
	v_bfe_i32 v2, v8, 4, 24
	v_and_b32_e32 v3, 0x1fffff0, v2
	v_lshrrev_b32_e32 v2, 1, v2
	v_and_b32_e32 v2, 4, v2
	v_lshlrev_b32_e32 v9, 4, v8
	v_or3_b32 v2, v3, v2, v0
	v_lshl_or_b32 v134, v2, 7, v1
	v_add_u32_e32 v2, 0x2000, v9
	v_ashrrev_i32_e32 v3, 8, v2
	v_and_b32_e32 v4, 0x1fffff0, v3
	v_lshrrev_b32_e32 v3, 1, v3
	v_and_b32_e32 v3, 4, v3
	v_or3_b32 v0, v4, v3, v0
	v_lshl_or_b32 v136, v0, 7, v1
	v_bfe_i32 v0, v8, 27, 1
	v_add_u32_sdwa v0, v9, v0 dst_sel:DWORD dst_unused:UNUSED_PAD src0_sel:DWORD src1_sel:BYTE_3
	v_ashrrev_i32_e32 v0, 8, v0
	v_mul_i32_i24_e32 v1, 0x100, v0
	v_sub_u32_e32 v1, v9, v1
	v_lshlrev_b32_e32 v3, 4, v0
	v_bitop3_b32 v1, v3, v1, s7 bitop3:0x6c
	v_ashrrev_i32_e32 v1, 1, v1
	v_lshl_add_u32 v138, v0, 7, v1
	v_ashrrev_i32_e32 v0, 31, v2
	v_add_u32_sdwa v0, v2, v0 dst_sel:DWORD dst_unused:UNUSED_PAD src0_sel:DWORD src1_sel:BYTE_3
	v_ashrrev_i32_e32 v0, 8, v0
	v_mul_i32_i24_e32 v1, 0x100, v0
	v_sub_u32_e32 v1, v2, v1
	v_lshlrev_b32_e32 v2, 4, v0
	v_bitop3_b32 v1, v2, v1, s7 bitop3:0x6c
	v_add_u32_e32 v6, 0x800, v162
	v_ashrrev_i32_e32 v1, 1, v1
	s_add_i32 s1, s1, 0x18000
	v_lshl_add_u32 v140, v0, 7, v1
	v_cndmask_b32_e32 v0, v6, v162, vcc
	s_cmp_lg_u32 0, -1
	v_ashrrev_i32_e32 v1, 31, v0
	s_cselect_b32 s14, 0, 0
	v_lshlrev_b64 v[0:1], 8, v[0:1]
	s_lshl_b32 s6, s6, 10
	v_ashrrev_i32_e32 v135, 31, v134
	v_lshl_add_u64 v[2:3], s[86:87], 0, v[0:1]
	s_add_i32 s6, s14, s6
	v_lshlrev_b64 v[52:53], 1, v[134:135]
	v_ashrrev_i32_e32 v137, 31, v136
	v_lshl_add_u64 v[4:5], v[2:3], 0, v[52:53]
	s_mov_b32 m0, s6
	v_lshlrev_b64 v[54:55], 1, v[136:137]
	v_ashrrev_i32_e32 v139, 31, v138
	global_load_lds_dwordx4 v[4:5], off
	v_lshl_add_u64 v[2:3], v[2:3], 0, v[54:55]
	s_add_i32 m0, s6, 0x2000
	v_lshl_add_u64 v[0:1], s[84:85], 0, v[0:1]
	v_lshlrev_b64 v[56:57], 1, v[138:139]
	v_ashrrev_i32_e32 v141, 31, v140
	global_load_lds_dwordx4 v[2:3], off
	s_add_i32 m0, s6, 0xc000
	v_lshl_add_u64 v[2:3], v[0:1], 0, v[56:57]
	v_lshlrev_b64 v[58:59], 1, v[140:141]
	v_sub_u32_e32 v166, v6, v161
	global_load_lds_dwordx4 v[2:3], off
	v_lshl_add_u64 v[0:1], v[0:1], 0, v[58:59]
	s_add_i32 m0, s6, 0xe000
	v_cndmask_b32_e32 v60, v166, v162, vcc
	global_load_lds_dwordx4 v[0:1], off
	v_or_b32_e32 v0, 64, v60
	v_ashrrev_i32_e32 v1, 31, v0
	v_lshlrev_b64 v[0:1], 8, v[0:1]
	v_lshl_add_u64 v[2:3], s[86:87], 0, v[0:1]
	s_add_i32 m0, s6, 0x4000
	v_lshl_add_u64 v[4:5], v[2:3], 0, v[52:53]
	global_load_lds_dwordx4 v[4:5], off
	v_lshl_add_u64 v[2:3], v[2:3], 0, v[54:55]
	s_add_i32 m0, s6, 0x6000
	v_lshl_add_u64 v[0:1], s[84:85], 0, v[0:1]
	global_load_lds_dwordx4 v[2:3], off
	s_add_i32 m0, s6, 0x10000
	v_lshl_add_u64 v[2:3], v[0:1], 0, v[56:57]
	v_lshlrev_b32_e32 v10, 8, v155
	v_and_b32_e32 v11, 0x70, v9
	global_load_lds_dwordx4 v[2:3], off
	v_lshl_add_u64 v[0:1], v[0:1], 0, v[58:59]
	s_add_i32 m0, s6, 0x12000
	v_bitop3_b32 v169, v178, v10, v11 bitop3:0xde
	global_load_lds_dwordx4 v[0:1], off
	v_add_u32_e32 v4, 0, v169
	s_waitcnt vmcnt(0)
	s_waitcnt vmcnt(0) lgkmcnt(0)
	s_barrier
; template <int DQK> __device__ __forceinline__ void qkt(f32x16& p0, f32x16& p1, const char* Ks, const bf16x8* qr, int r32, int hi) {
;     p0 = f32x16{}; p1 = f32x16{};
; #pragma unroll
;     for (int d0 = 0; d0 < DQK / 16; ++d0) { const int cb = (d0 * 16 + hi * 8) * 2;
;         const bf16x8 b0 = *reinterpret_cast<const bf16x8*>(Ks + kswz<DQK>(r32, cb));
;         const bf16x8 b1 = *reinterpret_cast<const bf16x8*>(Ks + kswz<DQK>(32 + r32, cb));
;         p0 = __builtin_amdgcn_mfma_f32_32x32x16_bf16(b0, qr[d0], p0, 0, 0, 0);
;         p1 = __builtin_amdgcn_mfma_f32_32x32x16_bf16(b1, qr[d0], p1, 0, 0, 0); }
; }
; template <int LDQ, int LDK, int LDV> ...
;     ...
;     f32x16 pA0, pA1, pB0, pB1; float mnA, mnB, alA, alB; bf16x8 pa0, pa1, pa2, pa3; const int NT = seq / 64;
;     STAGE(0, 0); STAGE(1, 64); asm volatile("s_waitcnt vmcnt(0)" ::: "memory"); __syncthreads();
;     qkt<DQK>(pA0, pA1, K_lds, qr, r32, hi); partialSM(pA0, pA1, m_reg, mnA, alA, C, thr_raw);
	ds_read_b128 v[0:3], v4 offset:49152
	ds_read_b128 v[4:7], v4 offset:57344
	s_waitcnt lgkmcnt(1)
	v_mfma_f32_32x32x16_bf16 v[32:47], v[0:3], v[124:127], 0
	v_or_b32_e32 v0, 32, v178
	v_bitop3_b32 v171, v0, v10, v11 bitop3:0xde
	v_and_b32_e32 v61, 63, v8
	v_lshlrev_b32_e32 v12, 3, v61
	s_add_i32 m0, s6, 0x8000
	s_mov_b32 s44, 0
	s_mov_b32 s45, s44
	s_waitcnt lgkmcnt(0)
	v_mfma_f32_32x32x16_bf16 v[16:31], v[4:7], v[124:127], 0
	v_add_u32_e32 v4, 0, v171
	ds_read_b128 v[0:3], v4 offset:49152
	ds_read_b128 v[4:7], v4 offset:57344
	s_mov_b32 s46, s44
	s_mov_b32 s47, s44
	s_mov_b32 s48, s44
	s_mov_b32 s49, s44
	s_mov_b32 s50, s44
	s_waitcnt lgkmcnt(1)
	v_mfma_f32_32x32x16_bf16 v[32:47], v[0:3], v[120:123], v[32:47]
	v_or_b32_e32 v0, 64, v178
	v_bitop3_b32 v170, v0, v10, v11 bitop3:0xde
	s_mov_b32 s51, s44
	s_mov_b32 s52, s44
	s_mov_b32 s53, s44
	s_mov_b32 s54, s44
	s_mov_b32 s55, s44
	s_waitcnt lgkmcnt(0)
	v_mfma_f32_32x32x16_bf16 v[16:31], v[4:7], v[120:123], v[16:31]
	v_add_u32_e32 v4, 0, v170
	ds_read_b128 v[0:3], v4 offset:49152
	ds_read_b128 v[4:7], v4 offset:57344
	s_mov_b32 s56, s44
	s_mov_b32 s57, s44
	s_mov_b32 s58, s44
	s_mov_b32 s59, s44
	v_cmp_gt_u32_e64 s[38:39], 32, v61
	s_waitcnt lgkmcnt(1)
	v_mfma_f32_32x32x16_bf16 v[32:47], v[0:3], v[116:119], v[32:47]
	v_or_b32_e32 v0, 0x60, v178
	v_bitop3_b32 v168, v0, v10, v11 bitop3:0xde
	s_mov_b32 s25, 2
	s_mov_b32 s7, 1
	s_mov_b32 s22, 4
	s_movk_i32 s23, 0x100
	v_lshl_add_u32 v157, v155, 2, s1
	s_waitcnt lgkmcnt(0)
	v_mfma_f32_32x32x16_bf16 v[16:31], v[4:7], v[116:119], v[16:31]
	v_add_u32_e32 v4, 0, v168
	ds_read_b128 v[0:3], v4 offset:49152
	ds_read_b128 v[4:7], v4 offset:57344
	s_waitcnt lgkmcnt(1)
	v_mfma_f32_32x32x16_bf16 v[32:47], v[0:3], v[112:115], v[32:47]
	v_or_b32_e32 v0, 0x80, v178
	v_bitop3_b32 v167, v0, v10, v11 bitop3:0xde
	s_waitcnt lgkmcnt(0)
	v_mfma_f32_32x32x16_bf16 v[16:31], v[4:7], v[112:115], v[16:31]
	v_add_u32_e32 v4, 0, v167
	ds_read_b128 v[0:3], v4 offset:49152
	ds_read_b128 v[4:7], v4 offset:57344
	s_waitcnt lgkmcnt(1)
	v_mfma_f32_32x32x16_bf16 v[32:47], v[0:3], v[108:111], v[32:47]
	v_or_b32_e32 v0, 0xa0, v178
	v_bitop3_b32 v163, v0, v10, v11 bitop3:0xde
	s_waitcnt lgkmcnt(0)
	v_mfma_f32_32x32x16_bf16 v[16:31], v[4:7], v[108:111], v[16:31]
	v_add_u32_e32 v4, 0, v163
	ds_read_b128 v[0:3], v4 offset:49152
	ds_read_b128 v[4:7], v4 offset:57344
	s_waitcnt lgkmcnt(1)
	v_mfma_f32_32x32x16_bf16 v[32:47], v[0:3], v[104:107], v[32:47]
	v_and_b32_e32 v0, 0xc0, v9
	v_and_or_b32 v9, v12, 24, v0
	v_or_b32_e32 v0, 0xc0, v178
	v_bitop3_b32 v164, v0, v10, v11 bitop3:0xde
	v_add_u32_e32 v13, 0, v164
	ds_read_b128 v[0:3], v13 offset:49152
	s_waitcnt lgkmcnt(1)
	v_mfma_f32_32x32x16_bf16 v[16:31], v[4:7], v[104:107], v[16:31]
	v_lshlrev_b32_e32 v4, 1, v8
	v_and_b32_e32 v4, 32, v4
	v_and_b32_e32 v5, 0x100, v12
	v_or3_b32 v4, v9, v4, v5
	v_add_u32_e32 v159, s14, v4
	ds_read_b128 v[4:7], v13 offset:57344
	s_waitcnt lgkmcnt(1)
	v_mfma_f32_32x32x16_bf16 v[32:47], v[0:3], v[100:103], v[32:47]
	v_or_b32_e32 v0, 0xe0, v178
	v_bitop3_b32 v165, v0, v10, v11 bitop3:0xde
	v_add_u32_e32 v8, 0, v165
	ds_read_b128 v[0:3], v8 offset:49152
	ds_read_b128 v[48:51], v8 offset:57344
	s_waitcnt lgkmcnt(2)
	v_mfma_f32_32x32x16_bf16 v[16:31], v[4:7], v[100:103], v[16:31]
	s_waitcnt lgkmcnt(0)
; __device__ __forceinline__ void partialSM(f32x16& p0, f32x16& p1, float& m_reg, float& mn, float& alpha, const float C, const float thr_raw) {
;     float pmax = p0[0];
; #pragma unroll
;     for (int r = 1; r < 16; ++r) pmax = fmaxf(pmax, p0[r]);
; #pragma unroll
;     for (int r = 0; r < 16; ++r) pmax = fmaxf(pmax, p1[r]);
;     { auto rr = __builtin_amdgcn_permlane32_swap(__float_as_uint(pmax), __float_as_uint(pmax), false, false);
;       pmax = fmaxf(__uint_as_float(rr[0]), __uint_as_float(rr[1])); }
;     if (__builtin_expect(__all(pmax - m_reg <= thr_raw), 1)) { mn = m_reg; alpha = 1.f; }
;     else { mn = fmaxf(m_reg, pmax); alpha = __builtin_amdgcn_exp2f((m_reg - mn) * C); m_reg = mn; }
;     const float mnC = -mn * C;
; #pragma unroll
;     for (int r = 0; r < 16; ++r) p0[r] = fmaf(p0[r], C, mnC);
; #pragma unroll
;     for (int r = 0; r < 16; ++r) p1[r] = fmaf(p1[r], C, mnC);
; #pragma unroll
;     for (int r = 0; r < 16; ++r) p0[r] = __builtin_amdgcn_exp2f(p0[r]);
; template <int LDQ, int LDK, int LDV> ...
;     ...
;     qkt<DQK>(pA0, pA1, K_lds, qr, r32, hi); partialSM(pA0, pA1, m_reg, mnA, alA, C, thr_raw);
;     STAGE(2, 128);
;     int bp = 0, bc = 1, bn = 2;
	v_mfma_f32_32x32x16_bf16 v[16:31], v[48:51], v[96:99], v[16:31]
	v_or_b32_e32 v48, 0x80, v60
	v_ashrrev_i32_e32 v49, 31, v48
	v_lshlrev_b64 v[48:49], 8, v[48:49]
	v_lshl_add_u64 v[50:51], s[86:87], 0, v[48:49]
	v_lshl_add_u64 v[52:53], v[50:51], 0, v[52:53]
	global_load_lds_dwordx4 v[52:53], off
	v_lshl_add_u64 v[50:51], v[50:51], 0, v[54:55]
	s_add_i32 m0, s6, 0xa000
	v_lshl_add_u64 v[48:49], s[84:85], 0, v[48:49]
	global_load_lds_dwordx4 v[50:51], off
	s_add_i32 m0, s6, 0x14000
	v_lshl_add_u64 v[50:51], v[48:49], 0, v[56:57]
	global_load_lds_dwordx4 v[50:51], off
	v_lshl_add_u64 v[48:49], v[48:49], 0, v[58:59]
	s_add_i32 m0, s6, 0x16000
	v_mfma_f32_32x32x16_bf16 v[32:47], v[0:3], v[96:99], v[32:47]
	global_load_lds_dwordx4 v[48:49], off
	v_mov_b64_e32 v[0:1], s[44:45]
	v_mov_b64_e32 v[14:15], s[58:59]
	v_mov_b64_e32 v[2:3], s[46:47]
	v_mov_b64_e32 v[4:5], s[48:49]
	v_mov_b64_e32 v[6:7], s[50:51]
	s_nop 5
	v_max_f32_e32 v62, v33, v33
	v_max_f32_e32 v63, v32, v32
	v_max_f32_e32 v48, v63, v62
	v_max3_f32 v48, v48, v34, v35
	v_max3_f32 v48, v48, v36, v37
	v_max3_f32 v48, v48, v38, v39
	v_max3_f32 v48, v48, v40, v41
	v_max3_f32 v48, v48, v42, v43
	v_max3_f32 v48, v48, v44, v45
	v_max3_f32 v48, v48, v46, v47
	v_max3_f32 v48, v48, v16, v17
	v_max3_f32 v48, v48, v18, v19
	v_max3_f32 v48, v48, v20, v21
	v_max3_f32 v48, v48, v22, v23
	v_max3_f32 v48, v48, v24, v25
	v_max3_f32 v48, v48, v26, v27
	v_max3_f32 v48, v48, v28, v29
	v_max3_f32 v48, v48, v30, v31
	v_mov_b32_e32 v49, v48
	s_nop 1
	v_permlane32_swap_b32_e32 v48, v49
	v_max_f32_e32 v49, v49, v49
	v_max_f32_e32 v48, v48, v48
	v_max_f32_e32 v48, v48, v49
	v_add_f32_e32 v49, 0x7149f2ca, v48
	v_cmp_ge_f32_e32 vcc, s20, v49
	s_cmp_eq_u64 vcc, exec
	v_max_f32_e32 v49, 0xf149f2ca, v48
	s_cselect_b64 vcc, -1, 0
	v_mov_b32_e32 v48, 0xf149f2ca
	v_cndmask_b32_e32 v172, v49, v48, vcc
	v_mul_f32_e32 v48, 0xbe0293ee, v172
	v_fmamk_f32 v32, v32, 0x3e0293ee, v48
	v_exp_f32_e32 v206, v32
	v_fmamk_f32 v32, v33, 0x3e0293ee, v48
	v_exp_f32_e32 v209, v32
	v_fmamk_f32 v32, v34, 0x3e0293ee, v48
	v_exp_f32_e32 v207, v32
	v_fmamk_f32 v32, v35, 0x3e0293ee, v48
	v_exp_f32_e32 v210, v32
	v_fmamk_f32 v32, v36, 0x3e0293ee, v48
	v_exp_f32_e32 v208, v32
	v_fmamk_f32 v32, v37, 0x3e0293ee, v48
	v_exp_f32_e32 v211, v32
	v_fmamk_f32 v32, v38, 0x3e0293ee, v48
	v_exp_f32_e32 v204, v32
	v_fmamk_f32 v32, v39, 0x3e0293ee, v48
	v_exp_f32_e32 v205, v32
	v_fmamk_f32 v32, v40, 0x3e0293ee, v48
	v_exp_f32_e32 v200, v32
	v_fmamk_f32 v32, v41, 0x3e0293ee, v48
	v_exp_f32_e32 v202, v32
	v_fmamk_f32 v32, v42, 0x3e0293ee, v48
	v_exp_f32_e32 v201, v32
	v_fmamk_f32 v32, v43, 0x3e0293ee, v48
	v_exp_f32_e32 v203, v32
	v_fmamk_f32 v32, v44, 0x3e0293ee, v48
	v_pk_fma_f32 v[146:147], v[22:23], s[8:9], v[48:49] op_sel_hi:[1,0,0]
	v_sub_f32_e32 v22, 0xf149f2ca, v49
	v_exp_f32_e32 v196, v32
	v_fmamk_f32 v32, v45, 0x3e0293ee, v48
	v_mul_f32_e32 v22, 0x3e0293ee, v22
	v_exp_f32_e32 v198, v32
	v_fmamk_f32 v32, v46, 0x3e0293ee, v48
	v_exp_f32_e32 v22, v22
	v_exp_f32_e32 v197, v32
	v_fmamk_f32 v32, v47, 0x3e0293ee, v48
	v_exp_f32_e32 v199, v32
	v_mov_b64_e32 v[8:9], s[52:53]
	v_mov_b64_e32 v[10:11], s[54:55]
	v_mov_b64_e32 v[12:13], s[56:57]
	v_pk_fma_f32 v[142:143], v[30:31], s[8:9], v[48:49] op_sel_hi:[1,0,0]
	v_pk_fma_f32 v[128:129], v[28:29], s[8:9], v[48:49] op_sel_hi:[1,0,0]
	v_pk_fma_f32 v[130:131], v[26:27], s[8:9], v[48:49] op_sel_hi:[1,0,0]
	v_pk_fma_f32 v[144:145], v[24:25], s[8:9], v[48:49] op_sel_hi:[1,0,0]
	v_pk_fma_f32 v[148:149], v[20:21], s[8:9], v[48:49] op_sel_hi:[1,0,0]
	v_pk_fma_f32 v[150:151], v[18:19], s[8:9], v[48:49] op_sel_hi:[1,0,0]
	v_pk_fma_f32 v[152:153], v[16:17], s[8:9], v[48:49] op_sel_hi:[1,0,0]
	v_cndmask_b32_e64 v173, v22, 1.0, vcc
	v_mov_b64_e32 v[62:63], v[14:15]
	v_mov_b64_e32 v[46:47], v[14:15]
	v_mov_b64_e32 v[30:31], v[14:15]
	s_mov_b64 s[46:47], 0
	v_mov_b64_e32 v[60:61], v[12:13]
	v_mov_b64_e32 v[58:59], v[10:11]
	v_mov_b64_e32 v[56:57], v[8:9]
	v_mov_b64_e32 v[54:55], v[6:7]
	v_mov_b64_e32 v[52:53], v[4:5]
	v_mov_b64_e32 v[50:51], v[2:3]
	v_mov_b64_e32 v[48:49], v[0:1]
	v_mov_b64_e32 v[44:45], v[12:13]
	v_mov_b64_e32 v[42:43], v[10:11]
	v_mov_b64_e32 v[40:41], v[8:9]
	v_mov_b64_e32 v[38:39], v[6:7]
	v_mov_b64_e32 v[36:37], v[4:5]
	v_mov_b64_e32 v[34:35], v[2:3]
	v_mov_b64_e32 v[32:33], v[0:1]
	v_mov_b64_e32 v[28:29], v[12:13]
	v_mov_b64_e32 v[26:27], v[10:11]
	v_mov_b64_e32 v[24:25], v[8:9]
	v_mov_b64_e32 v[22:23], v[6:7]
	v_mov_b64_e32 v[20:21], v[4:5]
	v_mov_b64_e32 v[18:19], v[2:3]
	v_mov_b64_e32 v[16:17], v[0:1]
	v_readfirstlane_b32 s100, v176
	s_lshr_b32 s100, s100, 6
	s_cmp_ge_u32 s100, 4
	s_cbranch_scc0 .Lprio_skip_0
	s_setprio 1
.Lprio_skip_0:
	s_branch .LBB0_3449
.LBB0_3447:
	s_or_b64 exec, exec, s[48:49]
	s_waitcnt lgkmcnt(0)
	v_add_u32_e32 v129, s1, v178
	ds_read_b128 v[144:147], v129 offset:224
	ds_read_b128 v[148:151], v129 offset:192
	ds_read_b128 v[196:199], v129 offset:160
	ds_read_b128 v[200:203], v129 offset:128
	s_waitcnt lgkmcnt(0)
	v_pk_mul_f32 v[12:13], v[12:13], v[144:145]
	v_pk_mul_f32 v[8:9], v[8:9], v[148:149]
	v_pk_mul_f32 v[4:5], v[4:5], v[196:197]
	v_pk_mul_f32 v[14:15], v[14:15], v[146:147]
	v_pk_mul_f32 v[10:11], v[10:11], v[150:151]
	v_pk_mul_f32 v[6:7], v[6:7], v[198:199]
	v_pk_mul_f32 v[2:3], v[2:3], v[202:203]
	v_pk_mul_f32 v[0:1], v[0:1], v[200:201]
	v_pk_mul_f32 v[60:61], v[60:61], v[144:145]
	v_pk_mul_f32 v[56:57], v[56:57], v[148:149]
	v_pk_mul_f32 v[52:53], v[52:53], v[196:197]
	v_pk_mul_f32 v[62:63], v[62:63], v[146:147]
	v_pk_mul_f32 v[58:59], v[58:59], v[150:151]
	v_pk_mul_f32 v[54:55], v[54:55], v[198:199]
	v_pk_mul_f32 v[50:51], v[50:51], v[202:203]
	v_pk_mul_f32 v[48:49], v[48:49], v[200:201]
	v_pk_mul_f32 v[44:45], v[44:45], v[144:145]
	v_pk_mul_f32 v[40:41], v[40:41], v[148:149]
	v_pk_mul_f32 v[36:37], v[36:37], v[196:197]
	v_pk_mul_f32 v[46:47], v[46:47], v[146:147]
	v_pk_mul_f32 v[42:43], v[42:43], v[150:151]
	v_pk_mul_f32 v[38:39], v[38:39], v[198:199]
	v_pk_mul_f32 v[34:35], v[34:35], v[202:203]
	v_pk_mul_f32 v[32:33], v[32:33], v[200:201]
	v_pk_mul_f32 v[28:29], v[28:29], v[144:145]
	v_pk_mul_f32 v[24:25], v[24:25], v[148:149]
	v_pk_mul_f32 v[20:21], v[20:21], v[196:197]
	v_pk_mul_f32 v[30:31], v[30:31], v[146:147]
	v_pk_mul_f32 v[26:27], v[26:27], v[150:151]
	v_pk_mul_f32 v[22:23], v[22:23], v[198:199]
	v_pk_mul_f32 v[18:19], v[18:19], v[202:203]
	v_pk_mul_f32 v[16:17], v[16:17], v[200:201]

; #define LAS __attribute__((address_space(3)))
; __device__ __forceinline__ int otid() { int t = threadIdx.x; asm volatile("" : "+v"(t)); return t; }
; __device__ __forceinline__ int v_rd_base(int lane) { return ((lane & 3) << 3) | (((lane >> 2) & 3) << 6) | (((lane >> 4) & 1) << 5) | (((lane >> 5) & 1) << 8); }
; template <int DQK, int LDQ, int LDK, int LDV> ...
;     constexpr int ND0 = DQK / 16, KCH = DQK / 64;
;     constexpr int SHM_V = 64 * 128 * 2, SHM_K = 64 * DQK * 2;
;     const int tid = otid(), wid = __builtin_amdgcn_readfirstlane(tid >> 6), lane = tid & 63, r32 = lane & 31, hi = lane >> 5;
;     char* V_lds = lds; char* K_lds = lds + 2 * SHM_V;
;     LAS unsigned char* ldsl = (LAS unsigned char*)(uintptr_t)lds;
;     float* wsl = (float*)(lds + 2 * SHM_V + 2 * SHM_K) + wid * 64; float* li_l = wsl; float* al_l = wsl + 32;
;     float m_reg = -1e30f, l_reg = 0; f32x16 o[4] = {}; bf16x8 qr[ND0];
;     const bf16_t* Qw = Qb + (size_t)(wid * 32 + r32) * LDQ + hi * 8;
; #pragma unroll
;     for (int d0 = 0; d0 < ND0; ++d0) qr[d0] = *reinterpret_cast<const bf16x8*>(Qw + (d0 < 8 ? d0 * 16 : qr_off + (d0 - 8) * 16));
;     int voff[2], koff[KCH];
; #pragma unroll
;     for (int i = 0; i < 2; ++i) { const int L = (tid + 512 * i) * 16, sub = L >> 9, within = L & 511; const int kk = (sub >> 2) * 8 + (within >> 6), c = (sub & 3) * 32 + ((within & 63) >> 1);
;         const int k = (kk & ~0xC) | ((kk & 4) << 1) | ((kk & 8) >> 1); voff[i] = k * LDV + c; }
; #pragma unroll
;     for (int i = 0; i < KCH; ++i) { const int L = (tid + 512 * i) * 16, row = L / (DQK * 2), cb = (L % (DQK * 2)) ^ ((row & 7) << 4), col = cb >> 1;
;         koff[i] = (DQK == 128 || col < 128) ? row * LDK + col : -(row * 64 + col - 128) - 1; }
;     const int vb0 = (int)(uintptr_t)V_lds + v_rd_base(lane);
.LBB0_3468:
	s_andn2_saveexec_b64 s[2:3], s[68:69]
	s_cbranch_execz .LBB0_3389
	s_movk_i32 s6, 0x7f
	v_cmp_lt_i32_e32 vcc, s6, v4
	s_movk_i32 s0, 0x80
	v_cmp_gt_i32_e64 s[0:1], s0, v4
	v_cndmask_b32_e32 v0, v4, v0, vcc
	v_cndmask_b32_e64 v1, 5, 2, vcc
	v_ashrrev_i32_e32 v2, v1, v0
	v_lshlrev_b32_e32 v1, 11, v2
	v_lshl_add_u32 v0, v2, 8, v224
	s_and_saveexec_b64 s[6:7], s[0:1]
	s_xor_b64 s[0:1], exec, s[6:7]
	v_lshlrev_b32_e32 v0, 11, v2
	v_lshlrev_b32_e32 v1, 8, v4
	s_movk_i32 s6, 0x700
	v_and_or_b32 v144, v1, s6, v0
	v_lshl_add_u32 v3, v2, 8, v224
	s_or_saveexec_b64 s[0:1], s[0:1]
	v_mov_b32_e32 v169, 0x800
	v_mov_b32_e32 v2, 34
	v_mov_b32_e32 v170, v0
	s_xor_b64 exec, exec, s[0:1]
	v_mov_b32_e32 v169, 0
	v_mov_b32_e32 v2, 2
	v_mov_b32_e32 v3, v0
	v_mov_b32_e32 v170, v1
	v_mov_b32_e32 v144, v0
	s_or_b64 exec, exec, s[0:1]
	v_lshrrev_b32_e32 v1, 3, v4
	v_cndmask_b32_e32 v1, v1, v4, vcc
	v_and_b32_e32 v1, 3, v1
	v_mov_b64_e32 v[4:5], s[80:81]
	v_mad_i64_i32 v[4:5], s[0:1], v144, s16, v[4:5]
	v_lshlrev_b32_e32 v178, 8, v1
	v_lshlrev_b32_e32 v166, 7, v1
	v_lshl_add_u64 v[6:7], v[4:5], 0, v[178:179]
	v_lshl_or_b32 v4, v1, 6, v226
	v_sub_u32_e32 v5, v4, v166
	v_mov_b32_e32 v4, v176
	v_mov_b32_e32 v147, v179
	v_readfirstlane_b32 s1, v4
	s_ashr_i32 s6, s1, 6
	v_and_b32_e32 v164, 31, v4
	s_lshl_b32 s0, s6, 5
	v_bfe_u32 v165, v4, 5, 1
	v_or_b32_e32 v8, s0, v164
	v_mad_i64_i32 v[6:7], s[22:23], v8, s16, v[6:7]
	v_lshlrev_b32_e32 v146, 4, v165
	v_lshl_add_u64 v[6:7], v[6:7], 0, v[146:147]
	global_load_dwordx4 v[140:143], v[6:7], off
	global_load_dwordx4 v[136:139], v[6:7], off offset:32
	global_load_dwordx4 v[132:135], v[6:7], off offset:64
	global_load_dwordx4 v[128:131], v[6:7], off offset:96
	global_load_dwordx4 v[124:127], v[6:7], off offset:128
	global_load_dwordx4 v[120:123], v[6:7], off offset:160
	global_load_dwordx4 v[116:119], v[6:7], off offset:192
	global_load_dwordx4 v[112:115], v[6:7], off offset:224
	v_lshlrev_b32_e32 v178, 1, v5
	v_lshl_add_u64 v[6:7], v[6:7], 0, v[178:179]
	global_load_dwordx4 v[108:111], v[6:7], off
	global_load_dwordx4 v[104:107], v[6:7], off offset:32
	global_load_dwordx4 v[100:103], v[6:7], off offset:64
	global_load_dwordx4 v[96:99], v[6:7], off offset:96
	v_lshlrev_b32_e32 v5, 4, v4
	s_mov_b32 s7, 0x2aaaaaab
	v_mul_hi_i32 v6, v5, s7
	v_lshrrev_b32_e32 v7, 31, v6
	v_ashrrev_i32_e32 v6, 6, v6
	v_add_u32_e32 v6, v6, v7
	v_mul_i32_i24_e32 v7, 0x180, v6
	v_sub_u32_e32 v7, v5, v7
	v_lshlrev_b32_e32 v8, 4, v6
	s_movk_i32 s7, 0x70
	v_bitop3_b32 v7, v8, v7, s7 bitop3:0x6c
	v_ashrrev_i32_e32 v7, 1, v7
	s_movk_i32 s7, 0x7f
	v_cmp_lt_i32_e32 vcc, s7, v7
	s_and_saveexec_b64 s[22:23], vcc
	s_xor_b64 s[38:39], exec, s[22:23]
	v_lshl_add_u32 v6, v6, 6, v7
	v_sub_u32_e32 v178, 0x7f, v6
	s_andn2_saveexec_b64 s[38:39], s[38:39]
	v_lshl_add_u32 v178, v6, 10, v7
	s_or_b64 exec, exec, s[38:39]
	v_add_u32_e32 v6, 0x2000, v5
	s_mov_b32 s7, 0x2aaaaaab
	v_mul_hi_i32 v7, v6, s7
	v_lshrrev_b32_e32 v8, 31, v7
	v_ashrrev_i32_e32 v7, 6, v7
	v_add_u32_e32 v7, v7, v8
	v_mul_i32_i24_e32 v8, 0x180, v7
	v_sub_u32_e32 v8, v6, v8
	v_lshlrev_b32_e32 v9, 4, v7
	s_movk_i32 s7, 0x70
	v_bitop3_b32 v8, v9, v8, s7 bitop3:0x6c
	v_ashrrev_i32_e32 v8, 1, v8
	s_movk_i32 s7, 0x7f
	v_cmp_lt_i32_e32 vcc, s7, v8
	s_and_saveexec_b64 s[22:23], vcc
	s_xor_b64 s[38:39], exec, s[22:23]
	v_lshl_add_u32 v7, v7, 6, v8
	v_sub_u32_e32 v148, 0x7f, v7
	s_andn2_saveexec_b64 s[38:39], s[38:39]
	v_lshl_add_u32 v148, v7, 10, v8
	s_or_b64 exec, exec, s[38:39]
	v_add_u32_e32 v8, 0x4000, v5
	s_mov_b32 s7, 0x2aaaaaab
	v_mul_hi_i32 v7, v8, s7
	v_lshrrev_b32_e32 v9, 31, v7
	v_ashrrev_i32_e32 v7, 6, v7
	v_add_u32_e32 v7, v7, v9
	v_mul_i32_i24_e32 v9, 0x180, v7
	v_sub_u32_e32 v8, v8, v9
	v_lshlrev_b32_e32 v9, 4, v7
	s_movk_i32 s7, 0x70
	v_bitop3_b32 v8, v9, v8, s7 bitop3:0x6c
	v_ashrrev_i32_e32 v8, 1, v8
	s_movk_i32 s7, 0x7f
	v_cmp_lt_i32_e32 vcc, s7, v8
	s_and_saveexec_b64 s[22:23], vcc
	s_xor_b64 s[38:39], exec, s[22:23]
	v_lshl_add_u32 v7, v7, 6, v8
	v_sub_u32_e32 v150, 0x7f, v7
	s_andn2_saveexec_b64 s[38:39], s[38:39]
	v_lshl_add_u32 v150, v7, 10, v8
	s_or_b64 exec, exec, s[38:39]
	v_lshlrev_b32_e32 v8, 9, v1
	v_mov_b32_e32 v9, v179
	v_lshl_add_u64 v[152:153], s[70:71], 0, v[8:9]
	v_and_b32_e32 v7, 0x60, v4
	v_lshrrev_b32_e32 v8, 1, v5
	v_bfe_u32 v1, v5, 6, 2
	v_and_or_b32 v7, v8, 24, v7
	v_lshrrev_b32_e32 v8, 5, v5
	v_ashrrev_i32_e32 v5, 8, v5
	v_and_or_b32 v1, v8, 8, v1
	v_and_b32_e32 v8, 0x3ffff0, v5
	v_lshrrev_b32_e32 v5, 1, v5
	v_and_b32_e32 v5, 4, v5
	v_or3_b32 v5, v8, v5, v1
	v_lshl_or_b32 v154, v5, 10, v7
	v_ashrrev_i32_e32 v5, 8, v6
	s_and_b32 s1, s1, 0x3fffffc0
	v_and_b32_e32 v6, 0x3ffff0, v5
	v_lshrrev_b32_e32 v5, 1, v5
	s_lshl_b32 s1, s1, 2
	v_and_b32_e32 v5, 4, v5
	s_add_i32 s1, s1, 0
	v_or3_b32 v1, v6, v5, v1
	s_add_i32 s1, s1, 0x14000
	v_lshl_or_b32 v156, v1, 10, v7
	v_ashrrev_i32_e32 v1, 31, v0
	s_lshl_b32 s6, s6, 10
	v_lshlrev_b64 v[6:7], 11, v[0:1]
	s_cmp_lg_u32 0, -1
	v_lshl_add_u64 v[6:7], v[152:153], 0, v[6:7]
	s_cselect_b32 s14, 0, 0
	v_ashrrev_i32_e32 v155, 31, v154
	s_add_i32 s6, s14, s6
	v_lshl_add_u64 v[8:9], v[154:155], 1, v[6:7]
	v_lshl_add_u64 v[8:9], v[8:9], 0, s[36:37]
	s_mov_b32 m0, s6
	v_ashrrev_i32_e32 v157, 31, v156
	global_load_lds_dwordx4 v[8:9], off
	v_lshl_add_u64 v[8:9], v[156:157], 1, v[6:7]
	v_lshlrev_b64 v[0:1], 7, v[0:1]
	v_lshl_add_u64 v[8:9], v[8:9], 0, s[36:37]
	s_add_i32 m0, s6, 0x2000
	v_lshl_add_u64 v[0:1], s[76:77], 0, v[0:1]
	v_not_b32_e32 v158, v178
	v_mov_b32_e32 v159, v179
; __device__ __forceinline__ int crow(int r, int hi) { return (r & 3) + 8 * (r >> 2) + 4 * hi; }
; #define SBAR() __builtin_amdgcn_sched_barrier(0)
; template <int DQK, int LDQ, int LDK, int LDV> ...
;     ...
;     const int NT = seq / 64;
;     STAGE(0, 0); asm volatile("s_waitcnt vmcnt(0)" ::: "memory"); __syncthreads();
;     for (int j = 0; j < NT; ++j) {
;         const int buf = j & 1;
;         if (j + 1 < NT) STAGE(buf ^ 1, (j + 1) * 64);
;         f32x16 p0, p1; float mn, al; bf16x8 pa0, pa1, pa2, pa3;
;         SBAR(); qkt<DQK>(p0, p1, K_lds + buf * SHM_K, qr, r32, hi);
;         partialSM(p0, p1, m_reg, mn, al, C, thr_raw);
;         if (__any(al < 1.f)) { if (hi == 0) al_l[r32] = al; asm volatile("s_waitcnt lgkmcnt(0)" ::: "memory");
; #pragma unroll
;             for (int d = 0; d < 4; ++d)
; #pragma unroll
;                 for (int r = 0; r < 16; ++r) o[d][r] *= al_l[crow(r, hi)]; }
	global_load_lds_dwordx4 v[8:9], off
	v_lshl_add_u64 v[8:9], v[178:179], 1, v[6:7]
	v_lshl_add_u64 v[10:11], v[158:159], 1, v[0:1]
	v_cmp_gt_i32_e64 s[40:41], 0, v178
	s_add_i32 m0, s6, 0x8000
	v_mov_b32_e32 v149, v179
	v_cndmask_b32_e64 v9, v9, v11, s[40:41]
	v_cndmask_b32_e64 v8, v8, v10, s[40:41]
	v_not_b32_e32 v160, v148
	v_mov_b32_e32 v161, v179
	global_load_lds_dwordx4 v[8:9], off
	v_lshl_add_u64 v[8:9], v[148:149], 1, v[6:7]
	v_lshl_add_u64 v[10:11], v[160:161], 1, v[0:1]
	v_cmp_gt_i32_e64 s[42:43], 0, v148
	v_mov_b32_e32 v151, v179
	v_not_b32_e32 v162, v150
	v_mov_b32_e32 v163, v179
	v_cndmask_b32_e64 v9, v9, v11, s[42:43]
	v_cndmask_b32_e64 v8, v8, v10, s[42:43]
	s_add_i32 m0, s6, 0xa000
	v_lshl_add_u64 v[6:7], v[150:151], 1, v[6:7]
	v_lshl_add_u64 v[0:1], v[162:163], 1, v[0:1]
	v_cmp_gt_i32_e64 s[44:45], 0, v150
	global_load_lds_dwordx4 v[8:9], off
	s_nop 0
	v_cndmask_b32_e64 v1, v7, v1, s[44:45]
	v_cndmask_b32_e64 v0, v6, v0, s[44:45]
	s_add_i32 m0, s6, 0xc000
	v_sub_u32_e32 v203, v3, v169
	global_load_lds_dwordx4 v[0:1], off
	v_lshlrev_b32_e32 v3, 4, v164
	v_and_b32_e32 v6, 0x70, v3
	s_movk_i32 s23, 0x60
	v_bitop3_b32 v199, v146, v6, s23 bitop3:0x36
	s_movk_i32 s23, 0x80
	v_bitop3_b32 v198, v146, v6, s23 bitop3:0x36
	s_movk_i32 s23, 0xa0
	v_bitop3_b32 v197, v146, v6, s23 bitop3:0x36
	s_movk_i32 s23, 0xc0
	v_bitop3_b32 v196, v146, v6, s23 bitop3:0x36
	s_movk_i32 s23, 0xe0
	v_and_b32_e32 v0, 63, v4
	v_bitop3_b32 v195, v146, v6, s23 bitop3:0x36
	s_movk_i32 s23, 0x100
	v_lshlrev_b32_e32 v1, 3, v0
	v_bitop3_b32 v194, v146, v6, s23 bitop3:0x36
	s_movk_i32 s23, 0x120
	v_lshlrev_b32_e32 v4, 4, v0
	v_lshlrev_b32_e32 v5, 1, v0
	v_and_b32_e32 v1, 0x118, v1
	v_bitop3_b32 v175, v146, v6, s23 bitop3:0x36
	s_movk_i32 s23, 0x140
	s_waitcnt vmcnt(0)
	v_and_b32_e32 v4, 0xc0, v4
	s_movk_i32 s22, 0x70
	v_bitop3_b32 v173, v146, v6, s23 bitop3:0x36
	s_movk_i32 s23, 0x160
	v_cmp_gt_u32_e64 s[38:39], 32, v0
	v_and_or_b32 v0, v5, 32, v1
	v_mov_b32_e32 v14, v179
	v_mov_b32_e32 v15, v179
	v_bitop3_b32 v202, v146, v3, s22 bitop3:0x78
	v_bitop3_b32 v201, v146, v6, 32 bitop3:0x36
	v_bitop3_b32 v200, v146, v6, 64 bitop3:0x36
	v_bitop3_b32 v172, v146, v6, s23 bitop3:0x36
	v_add3_u32 v167, v4, s14, v0
	v_add_u32_e32 v204, 1, v2
	v_mov_b32_e32 v0, v179
	v_mov_b32_e32 v1, v179
	v_mov_b32_e32 v2, v179
	v_mov_b32_e32 v3, v179
	v_mov_b32_e32 v4, v179
	v_mov_b32_e32 v5, v179
	v_mov_b32_e32 v6, v179
	v_mov_b32_e32 v7, v179
	v_mov_b32_e32 v8, v179
	v_mov_b32_e32 v9, v179
	v_mov_b32_e32 v10, v179
	v_mov_b32_e32 v11, v179
	v_mov_b32_e32 v12, v179
	v_mov_b32_e32 v13, v179
	v_mov_b64_e32 v[62:63], v[14:15]
	v_mov_b64_e32 v[46:47], v[14:15]
	v_mov_b64_e32 v[30:31], v[14:15]
	v_ashrrev_i32_e32 v145, 31, v144
	s_mov_b32 s7, 0
	v_mul_u32_u24_e32 v171, 0x180, v164
	s_mov_b32 s22, 64
	v_lshl_add_u32 v147, v164, 2, s1
	v_mov_b32_e32 v205, 0
	v_mov_b32_e32 v168, 0xf149f2ca
	s_mov_b64 s[48:49], 0
	v_mov_b64_e32 v[60:61], v[12:13]
	v_mov_b64_e32 v[58:59], v[10:11]
	v_mov_b64_e32 v[56:57], v[8:9]
	v_mov_b64_e32 v[54:55], v[6:7]
	v_mov_b64_e32 v[52:53], v[4:5]
	v_mov_b64_e32 v[50:51], v[2:3]
	v_mov_b64_e32 v[48:49], v[0:1]
	v_mov_b64_e32 v[44:45], v[12:13]
	v_mov_b64_e32 v[42:43], v[10:11]
	v_mov_b64_e32 v[40:41], v[8:9]
	v_mov_b64_e32 v[38:39], v[6:7]
	v_mov_b64_e32 v[36:37], v[4:5]
	v_mov_b64_e32 v[34:35], v[2:3]
	v_mov_b64_e32 v[32:33], v[0:1]
	v_mov_b64_e32 v[28:29], v[12:13]
	v_mov_b64_e32 v[26:27], v[10:11]
	v_mov_b64_e32 v[24:25], v[8:9]
	v_mov_b64_e32 v[22:23], v[6:7]
	v_mov_b64_e32 v[20:21], v[4:5]
	v_mov_b64_e32 v[18:19], v[2:3]
	v_mov_b64_e32 v[16:17], v[0:1]
	s_waitcnt vmcnt(0) lgkmcnt(0)
	s_barrier
	v_readfirstlane_b32 s100, v176
	s_lshr_b32 s100, s100, 6
	s_cmp_ge_u32 s100, 4
	s_cbranch_scc0 .Lprio_skip_1
	s_setprio 1
.Lprio_skip_1:
	s_branch .LBB0_3488
.LBB0_3486:
	s_or_b64 exec, exec, s[50:51]
	s_waitcnt lgkmcnt(0)
	v_add_u32_e32 v207, s1, v146
	ds_read_b128 v[208:211], v207 offset:224
	ds_read_b128 v[220:223], v207 offset:192
	ds_read_b128 v[228:231], v207 offset:160
	ds_read_b128 v[232:235], v207 offset:128
	s_waitcnt lgkmcnt(0)
	v_pk_mul_f32 v[12:13], v[12:13], v[208:209]
	v_pk_mul_f32 v[8:9], v[8:9], v[220:221]
	v_pk_mul_f32 v[4:5], v[4:5], v[228:229]
	v_pk_mul_f32 v[14:15], v[14:15], v[210:211]
	v_pk_mul_f32 v[10:11], v[10:11], v[222:223]
	v_pk_mul_f32 v[6:7], v[6:7], v[230:231]
	v_pk_mul_f32 v[2:3], v[2:3], v[234:235]
	v_pk_mul_f32 v[0:1], v[0:1], v[232:233]
	v_pk_mul_f32 v[60:61], v[60:61], v[208:209]
	v_pk_mul_f32 v[56:57], v[56:57], v[220:221]
	v_pk_mul_f32 v[52:53], v[52:53], v[228:229]
	v_pk_mul_f32 v[62:63], v[62:63], v[210:211]
	v_pk_mul_f32 v[58:59], v[58:59], v[222:223]
	v_pk_mul_f32 v[54:55], v[54:55], v[230:231]
	v_pk_mul_f32 v[50:51], v[50:51], v[234:235]
	v_pk_mul_f32 v[48:49], v[48:49], v[232:233]
	v_pk_mul_f32 v[44:45], v[44:45], v[208:209]
	v_pk_mul_f32 v[40:41], v[40:41], v[220:221]
	v_pk_mul_f32 v[36:37], v[36:37], v[228:229]
	v_pk_mul_f32 v[46:47], v[46:47], v[210:211]
	v_pk_mul_f32 v[42:43], v[42:43], v[222:223]
	v_pk_mul_f32 v[38:39], v[38:39], v[230:231]
	v_pk_mul_f32 v[34:35], v[34:35], v[234:235]
	v_pk_mul_f32 v[32:33], v[32:33], v[232:233]
	v_pk_mul_f32 v[28:29], v[28:29], v[208:209]
	v_pk_mul_f32 v[24:25], v[24:25], v[220:221]
	v_pk_mul_f32 v[20:21], v[20:21], v[228:229]
	v_pk_mul_f32 v[30:31], v[30:31], v[210:211]
	v_pk_mul_f32 v[26:27], v[26:27], v[222:223]
	v_pk_mul_f32 v[22:23], v[22:23], v[230:231]
	v_pk_mul_f32 v[18:19], v[18:19], v[234:235]
	v_pk_mul_f32 v[16:17], v[16:17], v[232:233]
